# in-proj GEMM epilogue: n=0/n=1 column pieces paired with v_permlane16_swap, 32 dwordx2 stores per lane become 16 dwordx4 stores
# speedup vs baseline: 1.0474x; 1.0138x over previous
.LBB0_1220:
	s_cmp_eq_u32 s94, 0
	v_readlane_b32 s0, v255, 22
	s_cselect_b32 s7, s43, s0
	v_readlane_b32 s0, v255, 21
	s_cselect_b32 s5, 0x1800, s82
	s_cselect_b32 s6, s42, s0
	v_and_b32_e32 v170, 1, v235
	v_mul_u32_u24_e32 v170, 24, v170
	v_lshl_add_u32 v164, v160, 1, v170
	v_mov_b32_e32 v165, 0
	v_mad_i64_i32 v[172:173], s[0:1], s5, v162, 0
	v_lshl_add_u64 v[172:173], v[172:173], 1, s[6:7]
	v_lshl_add_u64 v[174:175], v[172:173], 0, v[164:165]
	v_cvt_pk_bf16_f32 v128, v128, v129
	v_cvt_pk_bf16_f32 v129, v130, v131
	v_cvt_pk_bf16_f32 v130, v124, v125
	v_cvt_pk_bf16_f32 v131, v126, v127
	v_cvt_pk_bf16_f32 v120, v120, v121
	v_cvt_pk_bf16_f32 v121, v122, v123
	v_cvt_pk_bf16_f32 v122, v116, v117
	v_cvt_pk_bf16_f32 v123, v118, v119
	v_permlane16_swap_b32_e32 v128, v130
	v_permlane16_swap_b32_e32 v129, v131
	v_permlane16_swap_b32_e32 v120, v122
	v_permlane16_swap_b32_e32 v121, v123
	global_store_dwordx4 v[174:175], v[128:131], off
	global_store_dwordx4 v[174:175], v[120:123], off offset:256
	v_mad_i64_i32 v[176:177], s[0:1], s5, v158, 0
	v_lshl_add_u64 v[176:177], v[176:177], 1, s[6:7]
	v_lshl_add_u64 v[178:179], v[176:177], 0, v[164:165]
	v_cvt_pk_bf16_f32 v112, v112, v113
	v_cvt_pk_bf16_f32 v113, v114, v115
	v_cvt_pk_bf16_f32 v114, v108, v109
	v_cvt_pk_bf16_f32 v115, v110, v111
	v_cvt_pk_bf16_f32 v104, v104, v105
	v_cvt_pk_bf16_f32 v105, v106, v107
	v_cvt_pk_bf16_f32 v106, v100, v101
	v_cvt_pk_bf16_f32 v107, v102, v103
	v_permlane16_swap_b32_e32 v112, v114
	v_permlane16_swap_b32_e32 v113, v115
	v_permlane16_swap_b32_e32 v104, v106
	v_permlane16_swap_b32_e32 v105, v107
	global_store_dwordx4 v[178:179], v[112:115], off
	global_store_dwordx4 v[178:179], v[104:107], off offset:256
	v_mad_i64_i32 v[172:173], s[0:1], s5, v156, 0
	v_lshl_add_u64 v[172:173], v[172:173], 1, s[6:7]
	v_lshl_add_u64 v[174:175], v[172:173], 0, v[164:165]
	v_cvt_pk_bf16_f32 v96, v96, v97
	v_cvt_pk_bf16_f32 v97, v98, v99
	v_cvt_pk_bf16_f32 v98, v92, v93
	v_cvt_pk_bf16_f32 v99, v94, v95
	v_cvt_pk_bf16_f32 v88, v88, v89
	v_cvt_pk_bf16_f32 v89, v90, v91
	v_cvt_pk_bf16_f32 v90, v84, v85
	v_cvt_pk_bf16_f32 v91, v86, v87
	v_permlane16_swap_b32_e32 v96, v98
	v_permlane16_swap_b32_e32 v97, v99
	v_permlane16_swap_b32_e32 v88, v90
	v_permlane16_swap_b32_e32 v89, v91
	global_store_dwordx4 v[174:175], v[96:99], off
	global_store_dwordx4 v[174:175], v[88:91], off offset:256
	v_mad_i64_i32 v[176:177], s[0:1], s5, v154, 0
	v_lshl_add_u64 v[176:177], v[176:177], 1, s[6:7]
	v_lshl_add_u64 v[178:179], v[176:177], 0, v[164:165]
	v_cvt_pk_bf16_f32 v80, v80, v81
	v_cvt_pk_bf16_f32 v81, v82, v83
	v_cvt_pk_bf16_f32 v82, v76, v77
	v_cvt_pk_bf16_f32 v83, v78, v79
	v_cvt_pk_bf16_f32 v72, v72, v73
	v_cvt_pk_bf16_f32 v73, v74, v75
	v_cvt_pk_bf16_f32 v74, v68, v69
	v_cvt_pk_bf16_f32 v75, v70, v71
	v_permlane16_swap_b32_e32 v80, v82
	v_permlane16_swap_b32_e32 v81, v83
	v_permlane16_swap_b32_e32 v72, v74
	v_permlane16_swap_b32_e32 v73, v75
	global_store_dwordx4 v[178:179], v[80:83], off
	global_store_dwordx4 v[178:179], v[72:75], off offset:256
	v_mad_i64_i32 v[172:173], s[0:1], s5, v152, 0
	v_lshl_add_u64 v[172:173], v[172:173], 1, s[6:7]
	v_lshl_add_u64 v[174:175], v[172:173], 0, v[164:165]
	v_cvt_pk_bf16_f32 v64, v64, v65
	v_cvt_pk_bf16_f32 v65, v66, v67
	v_cvt_pk_bf16_f32 v66, v60, v61
	v_cvt_pk_bf16_f32 v67, v62, v63
	v_cvt_pk_bf16_f32 v56, v56, v57
	v_cvt_pk_bf16_f32 v57, v58, v59
	v_cvt_pk_bf16_f32 v58, v52, v53
	v_cvt_pk_bf16_f32 v59, v54, v55
	v_permlane16_swap_b32_e32 v64, v66
	v_permlane16_swap_b32_e32 v65, v67
	v_permlane16_swap_b32_e32 v56, v58
	v_permlane16_swap_b32_e32 v57, v59
	global_store_dwordx4 v[174:175], v[64:67], off
	global_store_dwordx4 v[174:175], v[56:59], off offset:256
	v_mad_i64_i32 v[176:177], s[0:1], s5, v138, 0
	v_lshl_add_u64 v[176:177], v[176:177], 1, s[6:7]
	v_lshl_add_u64 v[178:179], v[176:177], 0, v[164:165]
	v_cvt_pk_bf16_f32 v48, v48, v49
	v_cvt_pk_bf16_f32 v49, v50, v51
	v_cvt_pk_bf16_f32 v50, v44, v45
	v_cvt_pk_bf16_f32 v51, v46, v47
	v_cvt_pk_bf16_f32 v40, v40, v41
	v_cvt_pk_bf16_f32 v41, v42, v43
	v_cvt_pk_bf16_f32 v42, v36, v37
	v_cvt_pk_bf16_f32 v43, v38, v39
	v_permlane16_swap_b32_e32 v48, v50
	v_permlane16_swap_b32_e32 v49, v51
	v_permlane16_swap_b32_e32 v40, v42
	v_permlane16_swap_b32_e32 v41, v43
	global_store_dwordx4 v[178:179], v[48:51], off
	global_store_dwordx4 v[178:179], v[40:43], off offset:256
	v_mad_i64_i32 v[172:173], s[0:1], s5, v136, 0
	v_lshl_add_u64 v[172:173], v[172:173], 1, s[6:7]
	v_lshl_add_u64 v[174:175], v[172:173], 0, v[164:165]
	v_cvt_pk_bf16_f32 v32, v32, v33
	v_cvt_pk_bf16_f32 v33, v34, v35
	v_cvt_pk_bf16_f32 v34, v28, v29
	v_cvt_pk_bf16_f32 v35, v30, v31
	v_cvt_pk_bf16_f32 v24, v24, v25
	v_cvt_pk_bf16_f32 v25, v26, v27
	v_cvt_pk_bf16_f32 v26, v20, v21
	v_cvt_pk_bf16_f32 v27, v22, v23
	v_permlane16_swap_b32_e32 v32, v34
	v_permlane16_swap_b32_e32 v33, v35
	v_permlane16_swap_b32_e32 v24, v26
	v_permlane16_swap_b32_e32 v25, v27
	global_store_dwordx4 v[174:175], v[32:35], off
	global_store_dwordx4 v[174:175], v[24:27], off offset:256
	v_mad_i64_i32 v[176:177], s[0:1], s5, v2, 0
	v_lshl_add_u64 v[176:177], v[176:177], 1, s[6:7]
	v_lshl_add_u64 v[178:179], v[176:177], 0, v[164:165]
	v_cvt_pk_bf16_f32 v16, v16, v17
	v_cvt_pk_bf16_f32 v17, v18, v19
	v_cvt_pk_bf16_f32 v18, v12, v13
	v_cvt_pk_bf16_f32 v19, v14, v15
	v_cvt_pk_bf16_f32 v8, v8, v9
	v_cvt_pk_bf16_f32 v9, v10, v11
	v_cvt_pk_bf16_f32 v10, v4, v5
	v_cvt_pk_bf16_f32 v11, v6, v7
	v_permlane16_swap_b32_e32 v16, v18
	v_permlane16_swap_b32_e32 v17, v19
	v_permlane16_swap_b32_e32 v8, v10
	v_permlane16_swap_b32_e32 v9, v11
	global_store_dwordx4 v[178:179], v[16:19], off
	global_store_dwordx4 v[178:179], v[8:11], off offset:256
	s_and_b64 vcc, exec, s[38:39]
	s_mov_b64 s[6:7], -1
	s_cbranch_vccnz .LBB0_1177
